# phase-0 weight transpose tile: the four row loads and k-scale loads issued together (one exposed latency per tile instead of four)
# speedup vs baseline: 1.1093x; 1.0048x over previous
.LBB0_512:
	v_mov_b32_e32 v25, v196
	s_lshl_b32 s18, s23, 6
	v_lshlrev_b32_e32 v26, 2, v25
	v_and_b32_e32 v15, 60, v26
	v_ashrrev_i32_e32 v14, 4, v25
	v_lshlrev_b32_e32 v0, 2, v15
	v_lshl_add_u64 v[16:17], s[6:7], 0, v[0:1]
	v_add_u32_e32 v18, s18, v14
	v_cmp_gt_i32_e64 s[4:5], s2, v15
	v_ashrrev_i32_e32 v19, 31, v18
	v_mov_b32_e32 v228, 0
	v_mov_b32_e32 v229, 0
	v_mov_b32_e32 v230, 0
	v_mov_b32_e32 v231, 0
	v_mov_b32_e32 v232, 0
	v_mov_b32_e32 v233, 0
	v_mov_b32_e32 v234, 0
	v_mov_b32_e32 v235, 0
	v_mov_b32_e32 v236, 0
	v_mov_b32_e32 v237, 0
	v_mov_b32_e32 v238, 0
	v_mov_b32_e32 v239, 0
	v_mov_b32_e32 v240, 0
	v_mov_b32_e32 v241, 0
	v_mov_b32_e32 v242, 0
	v_mov_b32_e32 v243, 0
	v_mul_lo_u32 v0, s14, v19
	v_mul_lo_u32 v4, s15, v18
	v_mad_u64_u32 v[2:3], s[20:21], s14, v18, 0
	v_add3_u32 v3, v3, v0, v4
	v_lshl_add_u64 v[248:249], v[2:3], 2, v[16:17]
	s_lshl_b64 s[26:27], s[14:15], 6
	v_lshl_add_u64 v[250:251], v[248:249], 0, s[26:27]
	v_lshl_add_u64 v[252:253], v[250:251], 0, s[26:27]
	v_lshl_add_u64 v[254:255], v[252:253], 0, s[26:27]
	s_and_saveexec_b64 s[6:7], s[4:5]
	global_load_dwordx4 v[228:231], v[248:249], off
	global_load_dwordx4 v[232:235], v[250:251], off
	global_load_dwordx4 v[236:239], v[252:253], off
	global_load_dwordx4 v[240:243], v[254:255], off
	s_or_b64 exec, exec, s[6:7]
	s_cmp_eq_u64 s[16:17], 0
	s_cbranch_scc1 .Lwp_nosc
	v_lshl_add_u64 v[2:3], v[18:19], 2, s[16:17]
	global_load_dword v244, v[2:3], off
	global_load_dword v245, v[2:3], off offset:64
	global_load_dword v246, v[2:3], off offset:128
	global_load_dword v247, v[2:3], off offset:192
	s_waitcnt vmcnt(0)
	v_mul_f32_e32 v228, v228, v244
	v_mul_f32_e32 v229, v229, v244
	v_mul_f32_e32 v230, v230, v244
	v_mul_f32_e32 v231, v231, v244
	v_mul_f32_e32 v232, v232, v245
	v_mul_f32_e32 v233, v233, v245
	v_mul_f32_e32 v234, v234, v245
	v_mul_f32_e32 v235, v235, v245
	v_mul_f32_e32 v236, v236, v246
	v_mul_f32_e32 v237, v237, v246
	v_mul_f32_e32 v238, v238, v246
	v_mul_f32_e32 v239, v239, v246
	v_mul_f32_e32 v240, v240, v247
	v_mul_f32_e32 v241, v241, v247
	v_mul_f32_e32 v242, v242, v247
	v_mul_f32_e32 v243, v243, v247
.Lwp_nosc:
	s_waitcnt vmcnt(0)
	v_mul_u32_u24_e32 v0, 0x84, v15
	v_lshlrev_b32_e32 v2, 1, v14
	v_add3_u32 v18, 0, v0, v2
	v_cvt_pk_bf16_f32 v244, v228, v228
	ds_write_b16 v18, v244
	v_cvt_pk_bf16_f32 v245, v229, v229
	ds_write_b16 v18, v245 offset:132
	v_cvt_pk_bf16_f32 v246, v230, v230
	ds_write_b16 v18, v246 offset:264
	v_cvt_pk_bf16_f32 v247, v231, v231
	ds_write_b16 v18, v247 offset:396
	v_cvt_pk_bf16_f32 v244, v232, v232
	ds_write_b16 v18, v244 offset:32
	v_cvt_pk_bf16_f32 v245, v233, v233
	ds_write_b16 v18, v245 offset:164
	v_cvt_pk_bf16_f32 v246, v234, v234
	ds_write_b16 v18, v246 offset:296
	v_cvt_pk_bf16_f32 v247, v235, v235
	ds_write_b16 v18, v247 offset:428
	v_cvt_pk_bf16_f32 v244, v236, v236
	ds_write_b16 v18, v244 offset:64
	v_cvt_pk_bf16_f32 v245, v237, v237
	ds_write_b16 v18, v245 offset:196
	v_cvt_pk_bf16_f32 v246, v238, v238
	ds_write_b16 v18, v246 offset:328
	v_cvt_pk_bf16_f32 v247, v239, v239
	ds_write_b16 v18, v247 offset:460
	v_cvt_pk_bf16_f32 v244, v240, v240
	ds_write_b16 v18, v244 offset:96
	v_cvt_pk_bf16_f32 v245, v241, v241
	ds_write_b16 v18, v245 offset:228
	v_cvt_pk_bf16_f32 v246, v242, v242
	ds_write_b16 v18, v246 offset:360
	v_cvt_pk_bf16_f32 v247, v243, v243
	ds_write_b16 v18, v247 offset:492
	s_ashr_i32 s19, s18, 31
.LBB0_528:
.LBB0_529:
	s_lshl_b64 s[4:5], s[18:19], 1
	v_ashrrev_i32_e32 v14, 5, v25
	s_add_u32 s4, s12, s4
	s_movk_i32 s2, 0x84
	v_and_b32_e32 v0, 0x7c, v26
	s_addc_u32 s5, s13, s5
	s_waitcnt vmcnt(0)
	v_mul_lo_u32 v4, v14, s2
	v_lshl_add_u64 v[2:3], s[4:5], 0, v[0:1]
	v_add3_u32 v0, 0, v0, v4
	v_ashrrev_i32_e32 v4, 31, v14
	v_mul_lo_u32 v15, s10, v4
	v_mul_lo_u32 v16, s11, v14
	v_mad_u64_u32 v[4:5], s[4:5], s10, v14, 0
	v_add3_u32 v5, v5, v15, v16
	v_lshl_add_u64 v[4:5], v[4:5], 1, v[2:3]
	s_waitcnt lgkmcnt(0)
	s_barrier
	ds_read_b32 v15, v0
	ds_read_b32 v16, v0 offset:1056
	ds_read_b32 v17, v0 offset:2112
	ds_read_b32 v18, v0 offset:3168
	ds_read_b32 v19, v0 offset:4224
	ds_read_b32 v25, v0 offset:5280
	ds_read_b32 v26, v0 offset:6336
	ds_read_b32 v0, v0 offset:7392
	s_waitcnt lgkmcnt(7)
	global_store_dword v[4:5], v15, off
	v_add_u32_e32 v4, 8, v14
	v_ashrrev_i32_e32 v5, 31, v4
	v_mul_lo_u32 v15, s10, v5
	v_mul_lo_u32 v27, s11, v4
	v_mad_u64_u32 v[4:5], s[4:5], s10, v4, 0
	v_add3_u32 v5, v5, v15, v27
	v_lshl_add_u64 v[4:5], v[4:5], 1, v[2:3]
	s_waitcnt lgkmcnt(6)
	global_store_dword v[4:5], v16, off
	v_add_u32_e32 v4, 16, v14
	v_ashrrev_i32_e32 v5, 31, v4
	v_mul_lo_u32 v15, s10, v5
	v_mul_lo_u32 v16, s11, v4
	v_mad_u64_u32 v[4:5], s[4:5], s10, v4, 0
	v_add3_u32 v5, v5, v15, v16
	v_lshl_add_u64 v[4:5], v[4:5], 1, v[2:3]
	s_waitcnt lgkmcnt(5)
	global_store_dword v[4:5], v17, off
	v_add_u32_e32 v4, 24, v14
	v_ashrrev_i32_e32 v5, 31, v4
	v_mul_lo_u32 v15, s10, v5
	v_mul_lo_u32 v16, s11, v4
	v_mad_u64_u32 v[4:5], s[4:5], s10, v4, 0
	v_add3_u32 v5, v5, v15, v16
	v_lshl_add_u64 v[4:5], v[4:5], 1, v[2:3]
	s_waitcnt lgkmcnt(4)
	global_store_dword v[4:5], v18, off
	v_add_u32_e32 v4, 32, v14
	v_ashrrev_i32_e32 v5, 31, v4
	v_mul_lo_u32 v15, s10, v5
	v_mul_lo_u32 v16, s11, v4
	v_mad_u64_u32 v[4:5], s[4:5], s10, v4, 0
	v_add3_u32 v5, v5, v15, v16
	v_lshl_add_u64 v[4:5], v[4:5], 1, v[2:3]
	s_waitcnt lgkmcnt(3)
	global_store_dword v[4:5], v19, off
	v_add_u32_e32 v4, 40, v14
	v_ashrrev_i32_e32 v5, 31, v4
	v_mul_lo_u32 v15, s10, v5
	v_mul_lo_u32 v16, s11, v4
	v_mad_u64_u32 v[4:5], s[4:5], s10, v4, 0
	v_add3_u32 v5, v5, v15, v16
	v_lshl_add_u64 v[4:5], v[4:5], 1, v[2:3]
	s_waitcnt lgkmcnt(2)
	global_store_dword v[4:5], v25, off
	v_add_u32_e32 v4, 48, v14
	v_ashrrev_i32_e32 v5, 31, v4
	v_mul_lo_u32 v15, s10, v5
	v_mul_lo_u32 v16, s11, v4
	v_mad_u64_u32 v[4:5], s[4:5], s10, v4, 0
	v_add3_u32 v5, v5, v15, v16
	v_lshl_add_u64 v[4:5], v[4:5], 1, v[2:3]
	s_waitcnt lgkmcnt(1)
	global_store_dword v[4:5], v26, off
	v_add_u32_e32 v4, 56, v14
	v_ashrrev_i32_e32 v5, 31, v4
	v_mul_lo_u32 v14, s10, v5
	v_mul_lo_u32 v15, s11, v4
	v_mad_u64_u32 v[4:5], s[4:5], s10, v4, 0
	v_add3_u32 v5, v5, v14, v15
	v_lshl_add_u64 v[2:3], v[4:5], 1, v[2:3]
	s_mov_b64 s[4:5], 0
	s_waitcnt lgkmcnt(0)
	global_store_dword v[2:3], v0, off
	s_barrier
